# prologue phase: units handed out by eight per-XCD atomic counters (next index prefetched during the current unit) instead of the static blockIdx walk
# baseline (speedup 1.0000x reference)
.LBB0_580:
	v_readlane_b32 s0, v252, 23
	v_readlane_b32 s1, v252, 24
	v_mov_b32_e32 v36, v220
	s_andn2_b64 vcc, exec, s[0:1]
	s_cbranch_vccnz .LBB0_705
	v_and_b32_e32 v0, 15, v36
	s_movk_i32 s0, 0x3000
	v_cvt_f32_ubyte0_e32 v0, v0
	v_cmp_gt_i32_e64 s[38:39], s0, v36
	v_mul_f32_e32 v1, 0xbf549a78, v0
	s_mov_b32 s0, 0xc2fc0000
	v_cmp_gt_f32_e32 vcc, s0, v1
	s_waitcnt lgkmcnt(0)
	v_ashrrev_i32_e32 v37, 31, v36
	v_add_u32_e32 v48, 0xffe89000, v36
	v_cndmask_b32_e32 v1, 0, v124, vcc
	v_fmac_f32_e32 v1, 0xbf549a78, v0
	v_exp_f32_e32 v0, v1
	v_and_b32_e32 v1, 7, v36
	v_cvt_f32_ubyte0_e32 v1, v1
	v_mul_f32_e32 v2, 0xbfd49a78, v1
	v_cmp_gt_f32_e64 s[0:1], s0, v2
	v_ashrrev_i32_e32 v51, 6, v36
	v_add_u32_e32 v53, 0xffffff00, v36
	v_cndmask_b32_e64 v2, 0, v124, s[0:1]
	v_fmac_f32_e32 v2, 0xbfd49a78, v1
	v_exp_f32_e32 v1, v2
	v_cndmask_b32_e32 v2, 0, v125, vcc
	v_ldexp_f32 v49, v0, v2
	v_cndmask_b32_e64 v0, 0, v125, s[0:1]
	v_readlane_b32 s0, v253, 34
	v_ldexp_f32 v50, v1, v0
	v_lshlrev_b32_e32 v0, 2, v36
	v_readlane_b32 s1, v253, 35
	v_and_b32_e32 v52, 0xfc, v0
	v_lshl_add_u64 v[38:39], v[36:37], 4, s[0:1]
	v_mov_b32_e32 v102, 1
	v_readlane_b32 s0, v252, 13
	v_readlane_b32 s1, v252, 14
	s_getreg_b32 s2, hwreg(HW_REG_XCC_ID, 0, 4)
	s_lshl_b32 s2, s2, 5
	s_add_u32 s0, s0, s2
	s_addc_u32 s1, s1, 0
	v_cmp_eq_u32_e32 vcc, 0, v220
	s_and_saveexec_b64 s[2:3], vcc
	s_nop 2
	global_atomic_add v100, v193, v102, s[0:1] offset:512 sc0
	s_or_b64 exec, exec, s[2:3]
	v_cmp_eq_u32_e32 vcc, 0, v220
	s_and_saveexec_b64 s[2:3], vcc
	s_waitcnt vmcnt(0)
	ds_write_b32 v193, v100 offset:16
	s_or_b64 exec, exec, s[2:3]
	s_waitcnt lgkmcnt(0)
	s_barrier
	ds_read_b32 v101, v193 offset:16
	s_waitcnt lgkmcnt(0)
	s_barrier
	v_readfirstlane_b32 s5, v101
	s_getreg_b32 s2, hwreg(HW_REG_XCC_ID, 0, 4)
	s_lshl_b32 s5, s5, 3
	s_add_i32 s5, s5, s2
	s_cmpk_gt_i32 s5, 0x1d71
	s_cbranch_scc1 .LBB0_705
	v_readlane_b32 s0, v252, 13
	v_readlane_b32 s1, v252, 14
	s_getreg_b32 s2, hwreg(HW_REG_XCC_ID, 0, 4)
	s_lshl_b32 s2, s2, 5
	s_add_u32 s0, s0, s2
	s_addc_u32 s1, s1, 0
	v_cmp_eq_u32_e32 vcc, 0, v220
	s_and_saveexec_b64 s[2:3], vcc
	s_nop 2
	global_atomic_add v100, v193, v102, s[0:1] offset:512 sc0
	s_or_b64 exec, exec, s[2:3]
	s_branch .LBB0_583
.LBB0_582:
	v_cmp_eq_u32_e32 vcc, 0, v220
	s_and_saveexec_b64 s[2:3], vcc
	s_waitcnt vmcnt(0)
	ds_write_b32 v193, v100 offset:16
	s_or_b64 exec, exec, s[2:3]
	s_waitcnt lgkmcnt(0)
	s_barrier
	ds_read_b32 v101, v193 offset:16
	s_waitcnt lgkmcnt(0)
	s_barrier
	v_readfirstlane_b32 s5, v101
	s_getreg_b32 s2, hwreg(HW_REG_XCC_ID, 0, 4)
	s_lshl_b32 s5, s5, 3
	s_add_i32 s5, s5, s2
	s_cmpk_gt_i32 s5, 0x1d71
	s_cbranch_scc1 .LBB0_705
	v_readlane_b32 s0, v252, 13
	v_readlane_b32 s1, v252, 14
	s_getreg_b32 s2, hwreg(HW_REG_XCC_ID, 0, 4)
	s_lshl_b32 s2, s2, 5
	s_add_u32 s0, s0, s2
	s_addc_u32 s1, s1, 0
	v_cmp_eq_u32_e32 vcc, 0, v220
	s_and_saveexec_b64 s[2:3], vcc
	s_nop 2
	global_atomic_add v100, v193, v102, s[0:1] offset:512 sc0
	s_or_b64 exec, exec, s[2:3]
